# P0 rmsnorm: gain vectors loaded once before the row loop instead of three dependent reloads per row
# speedup vs baseline: 1.0152x; 1.0152x over previous
.LBB0_47:
	s_or_b64 exec, exec, s[6:7]
	s_cmpk_gt_i32 s16, 0x3fff
	s_cbranch_scc1 .LBB0_50
	v_lshlrev_b32_e32 v2, 4, v1
	v_mbcnt_lo_u32_b32 v1, -1, 0
	v_mbcnt_hi_u32_b32 v1, -1, v1
	v_and_b32_e32 v6, 64, v1
	v_add_u32_e32 v6, 64, v6
	v_xor_b32_e32 v7, 1, v1
	v_cmp_lt_i32_e32 vcc, v7, v6
	s_ashr_i32 s17, s16, 31
	s_lshl_b64 s[4:5], s[16:17], 11
	v_cndmask_b32_e32 v7, v1, v7, vcc
	v_lshlrev_b32_e32 v10, 2, v7
	v_xor_b32_e32 v7, 2, v1
	v_cmp_lt_i32_e32 vcc, v7, v6
	v_mov_b32_e32 v3, 0
	s_add_u32 s4, s20, s4
	v_cndmask_b32_e32 v7, v1, v7, vcc
	v_lshlrev_b32_e32 v11, 2, v7
	v_xor_b32_e32 v7, 4, v1
	v_cmp_lt_i32_e32 vcc, v7, v6
	s_addc_u32 s5, s21, s5
	s_ashr_i32 s19, s18, 31
	v_cndmask_b32_e32 v7, v1, v7, vcc
	v_lshlrev_b32_e32 v12, 2, v7
	v_xor_b32_e32 v7, 8, v1
	v_cmp_lt_i32_e32 vcc, v7, v6
	s_lshl_b64 s[6:7], s[18:19], 11
	v_lshl_add_u64 v[4:5], s[10:11], 0, v[2:3]
	v_cndmask_b32_e32 v7, v1, v7, vcc
	v_lshlrev_b32_e32 v13, 2, v7
	v_xor_b32_e32 v7, 16, v1
	v_cmp_lt_i32_e32 vcc, v7, v6
	v_mov_b32_e32 v16, 0x358637bd
	s_mov_b32 s3, 0xf800000
	v_cndmask_b32_e32 v7, v1, v7, vcc
	v_lshlrev_b32_e32 v14, 2, v7
	v_xor_b32_e32 v7, 32, v1
	v_cmp_lt_i32_e32 vcc, v7, v6
	v_mov_b32_e32 v17, 0x260
	s_movk_i32 s10, 0x7fff
	v_cndmask_b32_e32 v1, v1, v7, vcc
	v_lshlrev_b32_e32 v15, 2, v1
	v_mov_b32_e32 v1, v3
	v_lshl_add_u64 v[0:1], s[4:5], 0, v[0:1]
	s_mov_b64 s[4:5], 0x3000000
	v_lshl_add_u64 v[6:7], v[0:1], 0, s[4:5]
	s_lshl_b64 s[4:5], s[16:17], 12
	s_add_u32 s4, s8, s4
	s_addc_u32 s5, s9, s5
	v_lshl_add_u64 v[0:1], s[4:5], 0, v[2:3]
	s_mov_b64 s[4:5], 0xc00
	v_lshl_add_u64 v[8:9], v[0:1], 0, s[4:5]
	s_lshl_b64 s[8:9], s[18:19], 12
	v_mov_b32_e32 v18, 1
	global_load_dwordx4 v[64:67], v[4:5], off
	global_load_dwordx4 v[68:71], v[4:5], off offset:1024
	global_load_dwordx4 v[72:75], v[4:5], off offset:2048
	global_load_dwordx4 v[76:79], v[4:5], off offset:3072
	s_waitcnt vmcnt(0)
.LBB0_49:
	global_load_dwordx4 v[20:23], v[8:9], off offset:-3072
	global_load_dwordx4 v[24:27], v[8:9], off offset:-2048
	global_load_dwordx4 v[0:3], v[8:9], off
	global_load_dwordx4 v[28:31], v[8:9], off offset:-1024
	v_mov_b32_e32 v32, v64
	v_mov_b32_e32 v33, v65
	v_mov_b32_e32 v34, v66
	v_mov_b32_e32 v35, v67
	s_add_i32 s16, s16, s18
	v_lshl_add_u64 v[8:9], v[8:9], 0, s[8:9]
	s_cmpk_lt_i32 s16, 0x4000
	s_waitcnt vmcnt(3)
	v_pk_mul_f32 v[36:37], v[22:23], v[22:23]
	v_pk_mul_f32 v[38:39], v[20:21], v[20:21]
	s_waitcnt vmcnt(2)
	v_pk_mul_f32 v[40:41], v[26:27], v[26:27]
	v_pk_mul_f32 v[42:43], v[24:25], v[24:25]
	v_mov_b32_e32 v48, v20
	v_mov_b32_e32 v49, v22
	s_waitcnt vmcnt(0)
	v_mov_b32_e32 v50, v32
	v_mov_b32_e32 v51, v34
	v_mov_b32_e32 v22, v21
	v_mov_b32_e32 v34, v33
	v_pk_mov_b32 v[20:21], v[38:39], v[36:37] op_sel:[1,0]
	v_mov_b32_e32 v39, v37
	v_pk_mov_b32 v[32:33], v[42:43], v[40:41] op_sel:[1,0]
	v_mov_b32_e32 v43, v41
	v_mul_f32_e32 v45, v1, v1
	v_mul_f32_e32 v47, v2, v2
	v_mul_f32_e32 v44, v29, v29
	v_mul_f32_e32 v46, v31, v31
	v_pk_add_f32 v[20:21], v[20:21], v[38:39]
	v_pk_add_f32 v[32:33], v[32:33], v[42:43]
	v_mul_f32_e32 v19, v0, v0
	v_mul_f32_e32 v52, v3, v3
	v_pk_fma_f32 v[36:37], v[28:29], v[28:29], v[44:45] op_sel_hi:[1,1,0]
	v_pk_fma_f32 v[40:41], v[30:31], v[30:31], v[46:47] op_sel_hi:[1,1,0]
	v_pk_add_f32 v[20:21], v[20:21], v[20:21] op_sel:[0,1] op_sel_hi:[1,0]
	v_pk_add_f32 v[32:33], v[32:33], v[32:33] op_sel:[0,1] op_sel_hi:[1,0]
	v_mov_b32_e32 v37, v47
	v_mov_b32_e32 v41, v52
	v_mov_b32_e32 v21, v19
	v_mov_b32_e32 v33, v45
	v_pk_add_f32 v[36:37], v[36:37], v[40:41]
	v_pk_add_f32 v[20:21], v[20:21], v[32:33]
	s_nop 0
	v_pk_add_f32 v[20:21], v[20:21], v[36:37]
	s_nop 0
	v_add_f32_e32 v19, v20, v21
	ds_bpermute_b32 v20, v10, v19
	s_waitcnt lgkmcnt(0)
	v_add_f32_e32 v19, v19, v20
	ds_bpermute_b32 v20, v11, v19
	s_waitcnt lgkmcnt(0)
	v_add_f32_e32 v19, v19, v20
	ds_bpermute_b32 v20, v12, v19
	s_waitcnt lgkmcnt(0)
	v_add_f32_e32 v19, v19, v20
	ds_bpermute_b32 v20, v13, v19
	s_waitcnt lgkmcnt(0)
	v_add_f32_e32 v19, v19, v20
	ds_bpermute_b32 v20, v14, v19
	s_waitcnt lgkmcnt(0)
	v_add_f32_e32 v19, v19, v20
	ds_bpermute_b32 v20, v15, v19
	s_waitcnt lgkmcnt(0)
	v_add_f32_e32 v19, v19, v20
	v_fmamk_f32 v19, v19, 0x3a800000, v16
	v_mul_f32_e32 v20, 0x4f800000, v19
	v_cmp_gt_f32_e32 vcc, s3, v19
	s_nop 1
	v_cndmask_b32_e32 v19, v19, v20, vcc
	v_sqrt_f32_e32 v20, v19
	s_nop 0
	v_add_u32_e32 v21, -1, v20
	v_add_u32_e32 v32, 1, v20
	v_fma_f32 v33, -v21, v20, v19
	v_fma_f32 v36, -v32, v20, v19
	v_cmp_ge_f32_e64 s[4:5], 0, v33
	s_nop 1
	v_cndmask_b32_e64 v20, v20, v21, s[4:5]
	v_cmp_lt_f32_e64 s[4:5], 0, v36
	s_nop 1
	v_cndmask_b32_e64 v20, v20, v32, s[4:5]
	v_mul_f32_e32 v21, 0x37800000, v20
	v_cndmask_b32_e32 v20, v20, v21, vcc
	v_cmp_class_f32_e32 vcc, v19, v17
	s_nop 1
	v_cndmask_b32_e32 v19, v20, v19, vcc
	v_div_scale_f32 v20, s[4:5], v19, v19, 1.0
	v_rcp_f32_e32 v32, v20
	v_div_scale_f32 v21, vcc, 1.0, v19, 1.0
	v_fma_f32 v33, -v20, v32, 1.0
	v_fmac_f32_e32 v32, v33, v32
	v_mul_f32_e32 v33, v21, v32
	v_fma_f32 v36, -v20, v33, v21
	v_fmac_f32_e32 v33, v36, v32
	v_fma_f32 v20, -v20, v33, v21
	v_div_fmas_f32 v20, v20, v32, v33
	v_div_fixup_f32 v32, v20, v19, 1.0
	v_pk_mul_f32 v[20:21], v[48:49], v[32:33] op_sel_hi:[1,0]
	v_pk_mul_f32 v[22:23], v[22:23], v[32:33] op_sel_hi:[1,0]
	v_pk_mul_f32 v[20:21], v[50:51], v[20:21]
	v_pk_mul_f32 v[22:23], v[34:35], v[22:23]
	v_and_b32_sdwa v19, v21, v18 dst_sel:DWORD dst_unused:UNUSED_PAD src0_sel:WORD_1 src1_sel:DWORD
	v_and_b32_sdwa v34, v23, v18 dst_sel:DWORD dst_unused:UNUSED_PAD src0_sel:WORD_1 src1_sel:DWORD
	v_and_b32_sdwa v35, v22, v18 dst_sel:DWORD dst_unused:UNUSED_PAD src0_sel:WORD_1 src1_sel:DWORD
	v_and_b32_sdwa v33, v20, v18 dst_sel:DWORD dst_unused:UNUSED_PAD src0_sel:WORD_1 src1_sel:DWORD
	v_add3_u32 v19, v21, v19, s10
	v_add3_u32 v21, v23, v34, s10
	v_add3_u32 v22, v22, v35, s10
	v_add3_u32 v20, v20, v33, s10
	v_and_b32_e32 v21, 0xffff0000, v21
	v_and_b32_e32 v22, 0xffff0000, v22
	v_or_b32_sdwa v21, v21, v19 dst_sel:DWORD dst_unused:UNUSED_PAD src0_sel:DWORD src1_sel:WORD_1
	v_or_b32_sdwa v20, v22, v20 dst_sel:DWORD dst_unused:UNUSED_PAD src0_sel:DWORD src1_sel:WORD_1
	global_store_dwordx2 v[6:7], v[20:21], off
	v_mov_b32_e32 v20, v68
	v_mov_b32_e32 v21, v69
	v_mov_b32_e32 v22, v70
	v_mov_b32_e32 v23, v71
	v_mov_b32_e32 v34, v24
	v_mov_b32_e32 v35, v26
	v_mov_b32_e32 v26, v25
	v_pk_mul_f32 v[24:25], v[34:35], v[32:33] op_sel_hi:[1,0]
	v_pk_mul_f32 v[26:27], v[26:27], v[32:33] op_sel_hi:[1,0]
	v_mov_b32_e32 v34, v20
	v_mov_b32_e32 v35, v22
	v_mov_b32_e32 v22, v21
	v_pk_mul_f32 v[20:21], v[34:35], v[24:25]
	v_pk_mul_f32 v[22:23], v[22:23], v[26:27]
	v_and_b32_sdwa v19, v21, v18 dst_sel:DWORD dst_unused:UNUSED_PAD src0_sel:WORD_1 src1_sel:DWORD
	v_and_b32_sdwa v25, v23, v18 dst_sel:DWORD dst_unused:UNUSED_PAD src0_sel:WORD_1 src1_sel:DWORD
	v_and_b32_sdwa v26, v22, v18 dst_sel:DWORD dst_unused:UNUSED_PAD src0_sel:WORD_1 src1_sel:DWORD
	v_and_b32_sdwa v24, v20, v18 dst_sel:DWORD dst_unused:UNUSED_PAD src0_sel:WORD_1 src1_sel:DWORD
	v_add3_u32 v19, v21, v19, s10
	v_add3_u32 v21, v23, v25, s10
	v_add3_u32 v22, v22, v26, s10
	v_add3_u32 v20, v20, v24, s10
	v_and_b32_e32 v21, 0xffff0000, v21
	v_and_b32_e32 v22, 0xffff0000, v22
	v_or_b32_sdwa v21, v21, v19 dst_sel:DWORD dst_unused:UNUSED_PAD src0_sel:DWORD src1_sel:WORD_1
	v_or_b32_sdwa v20, v22, v20 dst_sel:DWORD dst_unused:UNUSED_PAD src0_sel:DWORD src1_sel:WORD_1
	global_store_dwordx2 v[6:7], v[20:21], off offset:512
	v_mov_b32_e32 v20, v72
	v_mov_b32_e32 v21, v73
	v_mov_b32_e32 v22, v74
	v_mov_b32_e32 v23, v75
	v_mov_b32_e32 v24, v28
	v_mov_b32_e32 v25, v30
	v_mov_b32_e32 v30, v29
	v_pk_mul_f32 v[24:25], v[24:25], v[32:33] op_sel_hi:[1,0]
	v_pk_mul_f32 v[26:27], v[30:31], v[32:33] op_sel_hi:[1,0]
	v_mov_b32_e32 v28, v20
	v_mov_b32_e32 v29, v22
	v_mov_b32_e32 v22, v21
	v_pk_mul_f32 v[20:21], v[28:29], v[24:25]
	v_pk_mul_f32 v[22:23], v[22:23], v[26:27]
	v_and_b32_sdwa v19, v21, v18 dst_sel:DWORD dst_unused:UNUSED_PAD src0_sel:WORD_1 src1_sel:DWORD
	v_and_b32_sdwa v25, v23, v18 dst_sel:DWORD dst_unused:UNUSED_PAD src0_sel:WORD_1 src1_sel:DWORD
	v_and_b32_sdwa v26, v22, v18 dst_sel:DWORD dst_unused:UNUSED_PAD src0_sel:WORD_1 src1_sel:DWORD
	v_and_b32_sdwa v24, v20, v18 dst_sel:DWORD dst_unused:UNUSED_PAD src0_sel:WORD_1 src1_sel:DWORD
	v_add3_u32 v19, v21, v19, s10
	v_add3_u32 v21, v23, v25, s10
	v_add3_u32 v22, v22, v26, s10
	v_add3_u32 v20, v20, v24, s10
	v_and_b32_e32 v21, 0xffff0000, v21
	v_and_b32_e32 v22, 0xffff0000, v22
	v_or_b32_sdwa v21, v21, v19 dst_sel:DWORD dst_unused:UNUSED_PAD src0_sel:DWORD src1_sel:WORD_1
	v_or_b32_sdwa v20, v22, v20 dst_sel:DWORD dst_unused:UNUSED_PAD src0_sel:DWORD src1_sel:WORD_1
	global_store_dwordx2 v[6:7], v[20:21], off offset:1024
	v_mov_b32_e32 v20, v76
	v_mov_b32_e32 v21, v77
	v_mov_b32_e32 v22, v78
	v_mov_b32_e32 v23, v79
	v_mov_b32_e32 v24, v0
	v_mov_b32_e32 v25, v2
	v_mov_b32_e32 v2, v1
	v_pk_mul_f32 v[0:1], v[24:25], v[32:33] op_sel_hi:[1,0]
	v_pk_mul_f32 v[2:3], v[2:3], v[32:33] op_sel_hi:[1,0]
	v_mov_b32_e32 v25, v22
	v_mov_b32_e32 v22, v21
	v_mov_b32_e32 v24, v20
	v_pk_mul_f32 v[2:3], v[22:23], v[2:3]
	v_pk_mul_f32 v[0:1], v[24:25], v[0:1]
	v_and_b32_sdwa v21, v3, v18 dst_sel:DWORD dst_unused:UNUSED_PAD src0_sel:WORD_1 src1_sel:DWORD
	v_and_b32_sdwa v22, v2, v18 dst_sel:DWORD dst_unused:UNUSED_PAD src0_sel:WORD_1 src1_sel:DWORD
	v_and_b32_sdwa v19, v1, v18 dst_sel:DWORD dst_unused:UNUSED_PAD src0_sel:WORD_1 src1_sel:DWORD
	v_and_b32_sdwa v20, v0, v18 dst_sel:DWORD dst_unused:UNUSED_PAD src0_sel:WORD_1 src1_sel:DWORD
	v_add3_u32 v3, v3, v21, s10
	v_add3_u32 v2, v2, v22, s10
	v_add3_u32 v0, v0, v20, s10
	v_add3_u32 v1, v1, v19, s10
	v_and_b32_e32 v3, 0xffff0000, v3
	v_and_b32_e32 v2, 0xffff0000, v2
	v_or_b32_sdwa v1, v3, v1 dst_sel:DWORD dst_unused:UNUSED_PAD src0_sel:DWORD src1_sel:WORD_1
	v_or_b32_sdwa v0, v2, v0 dst_sel:DWORD dst_unused:UNUSED_PAD src0_sel:DWORD src1_sel:WORD_1
	global_store_dwordx2 v[6:7], v[0:1], off offset:1536
	v_lshl_add_u64 v[6:7], v[6:7], 0, s[6:7]
	s_cbranch_scc1 .LBB0_49
